# K-loop load segments slimmed: B-fragment reads from one precomputed base VGPR, literal M0 values, M0-hazard nops replaced by interleaved LDS reads (8 fewer instructions per A+B segment, 6 fewer per A-
# baseline (speedup 1.0000x reference)
.LBB0_415:
	v_add_u32_e32 v244, 0x10000, v3
	v_writelane_b32 v250, s5, 0
	v_writelane_b32 v250, s23, 1
	v_writelane_b32 v250, s26, 2
	v_writelane_b32 v250, s27, 3
	v_writelane_b32 v250, s28, 4
	v_writelane_b32 v250, s29, 5
	v_writelane_b32 v250, s42, 6
	v_writelane_b32 v250, s43, 7
	v_writelane_b32 v250, s44, 8
	v_writelane_b32 v250, s45, 9
	v_writelane_b32 v250, s46, 10
	v_writelane_b32 v250, s47, 11
	v_writelane_b32 v250, s48, 12
	v_writelane_b32 v250, s49, 13
	v_writelane_b32 v250, s50, 14
	v_writelane_b32 v250, s51, 15
	v_writelane_b32 v250, s53, 16
	v_writelane_b32 v250, s54, 17
	v_writelane_b32 v250, s55, 18
	v_writelane_b32 v250, s56, 19
	v_writelane_b32 v250, s57, 20
	v_writelane_b32 v250, s58, 21
	v_writelane_b32 v250, s59, 22
	v_writelane_b32 v250, s60, 23
	v_writelane_b32 v250, s61, 24
	v_writelane_b32 v250, s63, 25
	v_writelane_b32 v250, s64, 26
	v_writelane_b32 v250, s65, 27
	s_add_i32 s53, s90, 0x80
	s_add_i32 s54, s52, -4
	s_add_i32 s55, s52, -3
	s_mov_b32 s56, s48
	s_add_i32 s57, s56, 0x2000
	s_add_i32 s58, s56, 0x4000
	s_add_i32 s59, s56, 0x6000
	s_add_i32 s60, s56, 0x8000
	s_add_i32 s61, s56, 0xa000
	v_readfirstlane_b32 s42, v6
	v_readfirstlane_b32 s43, v7
	v_readfirstlane_b32 s28, v4
	v_readfirstlane_b32 s29, v5
	v_readfirstlane_b32 s26, v146
	v_readfirstlane_b32 s5, v147
	v_readfirstlane_b32 s27, v148
	v_readfirstlane_b32 s23, v149
	s_add_u32 s28, s28, 0x100
	s_addc_u32 s29, s29, 0
	s_mov_b32 s63, -2
	v_mov_b32_e32 v4, 0
	s_add_u32 s44, s42, 0x100
	s_addc_u32 s45, s43, 0
	s_cmp_eq_u32 s63, s54
	s_cselect_b32 s50, s26, s44
	s_cselect_b32 s51, s5, s45
	s_cselect_b32 s48, s27, s28
	s_cselect_b32 s49, s23, s29
	s_add_u32 s46, s42, 0x80
	s_addc_u32 s47, s43, 0
	s_mov_b32 m0, s60
	s_add_u32 s42, s42, s53
	s_addc_u32 s43, s43, 0
	global_load_lds_dwordx4 v0, s[46:47]
	s_mov_b32 m0, s61
	ds_read_b128 v[164:167], v244
	global_load_lds_dwordx4 v142, s[46:47]
	ds_read_b128 v[168:171], v244 offset:1024
	ds_read_b128 v[188:191], v244 offset:2048
	ds_read_b128 v[192:195], v244 offset:3072
	ds_read_b128 v[196:199], v244 offset:16384
	ds_read_b128 v[200:203], v244 offset:17408
	ds_read_b128 v[204:207], v244 offset:18432
	ds_read_b128 v[208:211], v244 offset:19456
	s_add_i32 m0, s56, 0xc000
	ds_read_b128 v[212:215], v160
	global_load_lds_dwordx4 v0, s[42:43]
	s_add_i32 m0, s56, 0xe000
	ds_read_b128 v[216:219], v160 offset:1024
	global_load_lds_dwordx4 v142, s[42:43]
	ds_read_b128 v[220:223], v160 offset:2048
	ds_read_b128 v[224:227], v160 offset:3072
	ds_read_b128 v[228:231], v160 offset:4096
	ds_read_b128 v[232:235], v160 offset:5120
	ds_read_b128 v[236:239], v160 offset:6144
	ds_read_b128 v[240:243], v160 offset:7168
	s_waitcnt vmcnt(8)
	s_waitcnt lgkmcnt(8)
	s_barrier
	s_setprio 1
	s_waitcnt lgkmcnt(0)
	v_mfma_f32_16x16x32_bf16 v[128:131], v[164:167], v[212:215], 0
	v_mfma_f32_16x16x32_bf16 v[124:127], v[188:191], v[212:215], 0
	v_mfma_f32_16x16x32_bf16 v[112:115], v[164:167], v[220:223], 0
	v_mfma_f32_16x16x32_bf16 v[108:111], v[188:191], v[220:223], 0
	v_mfma_f32_16x16x32_bf16 v[96:99], v[164:167], v[228:231], 0
	v_mfma_f32_16x16x32_bf16 v[92:95], v[188:191], v[228:231], 0
	v_mfma_f32_16x16x32_bf16 v[80:83], v[164:167], v[236:239], 0
	v_mfma_f32_16x16x32_bf16 v[76:79], v[188:191], v[236:239], 0
	v_mfma_f32_16x16x32_bf16 v[128:131], v[168:171], v[216:219], v[128:131]
	v_mfma_f32_16x16x32_bf16 v[124:127], v[192:195], v[216:219], v[124:127]
	v_mfma_f32_16x16x32_bf16 v[112:115], v[168:171], v[224:227], v[112:115]
	v_mfma_f32_16x16x32_bf16 v[108:111], v[192:195], v[224:227], v[108:111]
	v_mfma_f32_16x16x32_bf16 v[96:99], v[168:171], v[232:235], v[96:99]
	v_mfma_f32_16x16x32_bf16 v[92:95], v[192:195], v[232:235], v[92:95]
	v_mfma_f32_16x16x32_bf16 v[80:83], v[168:171], v[240:243], v[80:83]
	v_mfma_f32_16x16x32_bf16 v[76:79], v[192:195], v[240:243], v[76:79]
	s_setprio 0
	s_setprio 1
	v_mfma_f32_16x16x32_bf16 v[120:123], v[196:199], v[212:215], 0
	v_mfma_f32_16x16x32_bf16 v[116:119], v[204:207], v[212:215], 0
	v_mfma_f32_16x16x32_bf16 v[104:107], v[196:199], v[220:223], 0
	v_mfma_f32_16x16x32_bf16 v[100:103], v[204:207], v[220:223], 0
	v_mfma_f32_16x16x32_bf16 v[88:91], v[196:199], v[228:231], 0
	v_mfma_f32_16x16x32_bf16 v[84:87], v[204:207], v[228:231], 0
	v_mfma_f32_16x16x32_bf16 v[72:75], v[196:199], v[236:239], 0
	v_mfma_f32_16x16x32_bf16 v[68:71], v[204:207], v[236:239], 0
	v_mfma_f32_16x16x32_bf16 v[120:123], v[200:203], v[216:219], v[120:123]
	v_mfma_f32_16x16x32_bf16 v[116:119], v[208:211], v[216:219], v[116:119]
	v_mfma_f32_16x16x32_bf16 v[104:107], v[200:203], v[224:227], v[104:107]
	v_mfma_f32_16x16x32_bf16 v[100:103], v[208:211], v[224:227], v[100:103]
	v_mfma_f32_16x16x32_bf16 v[88:91], v[200:203], v[232:235], v[88:91]
	v_mfma_f32_16x16x32_bf16 v[84:87], v[208:211], v[232:235], v[84:87]
	v_mfma_f32_16x16x32_bf16 v[72:75], v[200:203], v[240:243], v[72:75]
	v_mfma_f32_16x16x32_bf16 v[68:71], v[208:211], v[240:243], v[68:71]
	s_setprio 0
	s_barrier
	s_add_i32 m0, s69, 0x10000
	s_add_u32 s42, s48, s90
	s_addc_u32 s43, s49, 0
	global_load_lds_dwordx4 v140, s[48:49]
	s_add_i32 m0, s69, 0x12000
	ds_read_b128 v[212:215], v160 offset:16384
	global_load_lds_dwordx4 v144, s[48:49]
	s_add_i32 m0, s69, 0x14000
	ds_read_b128 v[216:219], v160 offset:17408
	global_load_lds_dwordx4 v140, s[42:43]
	s_add_i32 m0, s69, 0x16000
	ds_read_b128 v[220:223], v160 offset:18432
	global_load_lds_dwordx4 v144, s[42:43]
	ds_read_b128 v[224:227], v160 offset:19456
	ds_read_b128 v[228:231], v160 offset:20480
	ds_read_b128 v[232:235], v160 offset:21504
	ds_read_b128 v[236:239], v160 offset:22528
	ds_read_b128 v[240:243], v160 offset:23552
	s_waitcnt vmcnt(6)
	s_waitcnt lgkmcnt(0)
	s_barrier
	s_setprio 1
	s_waitcnt lgkmcnt(0)
	v_mfma_f32_16x16x32_bf16 v[64:67], v[164:167], v[212:215], 0
	v_mfma_f32_16x16x32_bf16 v[60:63], v[188:191], v[212:215], 0
	v_mfma_f32_16x16x32_bf16 v[48:51], v[164:167], v[220:223], 0
	v_mfma_f32_16x16x32_bf16 v[44:47], v[188:191], v[220:223], 0
	v_mfma_f32_16x16x32_bf16 v[32:35], v[164:167], v[228:231], 0
	v_mfma_f32_16x16x32_bf16 v[28:31], v[188:191], v[228:231], 0
	v_mfma_f32_16x16x32_bf16 v[16:19], v[164:167], v[236:239], 0
	v_mfma_f32_16x16x32_bf16 v[12:15], v[188:191], v[236:239], 0
	v_mfma_f32_16x16x32_bf16 v[64:67], v[168:171], v[216:219], v[64:67]
	v_mfma_f32_16x16x32_bf16 v[60:63], v[192:195], v[216:219], v[60:63]
	v_mfma_f32_16x16x32_bf16 v[48:51], v[168:171], v[224:227], v[48:51]
	v_mfma_f32_16x16x32_bf16 v[44:47], v[192:195], v[224:227], v[44:47]
	v_mfma_f32_16x16x32_bf16 v[32:35], v[168:171], v[232:235], v[32:35]
	v_mfma_f32_16x16x32_bf16 v[28:31], v[192:195], v[232:235], v[28:31]
	v_mfma_f32_16x16x32_bf16 v[16:19], v[168:171], v[240:243], v[16:19]
	v_mfma_f32_16x16x32_bf16 v[12:15], v[192:195], v[240:243], v[12:15]
	s_setprio 0
	s_setprio 1
	v_mfma_f32_16x16x32_bf16 v[56:59], v[196:199], v[212:215], 0
	v_mfma_f32_16x16x32_bf16 v[52:55], v[204:207], v[212:215], 0
	v_mfma_f32_16x16x32_bf16 v[40:43], v[196:199], v[220:223], 0
	v_mfma_f32_16x16x32_bf16 v[36:39], v[204:207], v[220:223], 0
	v_mfma_f32_16x16x32_bf16 v[24:27], v[196:199], v[228:231], 0
	v_mfma_f32_16x16x32_bf16 v[20:23], v[204:207], v[228:231], 0
	v_mfma_f32_16x16x32_bf16 v[8:11], v[196:199], v[236:239], 0
	v_mfma_f32_16x16x32_bf16 v[4:7], v[204:207], v[236:239], 0
	v_mfma_f32_16x16x32_bf16 v[56:59], v[200:203], v[216:219], v[56:59]
	v_mfma_f32_16x16x32_bf16 v[52:55], v[208:211], v[216:219], v[52:55]
	v_mfma_f32_16x16x32_bf16 v[40:43], v[200:203], v[224:227], v[40:43]
	v_mfma_f32_16x16x32_bf16 v[36:39], v[208:211], v[224:227], v[36:39]
	v_mfma_f32_16x16x32_bf16 v[24:27], v[200:203], v[232:235], v[24:27]
	v_mfma_f32_16x16x32_bf16 v[20:23], v[208:211], v[232:235], v[20:23]
	v_mfma_f32_16x16x32_bf16 v[8:11], v[200:203], v[240:243], v[8:11]
	v_mfma_f32_16x16x32_bf16 v[4:7], v[208:211], v[240:243], v[4:7]
	s_setprio 0
	s_barrier
	s_mov_b32 m0, s56
	s_add_u32 s42, s50, s90
	s_addc_u32 s43, s51, 0
	global_load_lds_dwordx4 v0, s[50:51]
	s_mov_b32 m0, s57
	ds_read_b128 v[164:167], v244 offset:32768
	global_load_lds_dwordx4 v142, s[50:51]
	ds_read_b128 v[168:171], v244 offset:33792
	ds_read_b128 v[188:191], v244 offset:34816
	ds_read_b128 v[192:195], v244 offset:35840
	ds_read_b128 v[196:199], v244 offset:49152
	ds_read_b128 v[200:203], v244 offset:50176
	ds_read_b128 v[204:207], v244 offset:51200
	ds_read_b128 v[208:211], v244 offset:52224
	s_mov_b32 m0, s58
	ds_read_b128 v[212:215], v160 offset:32768
	global_load_lds_dwordx4 v0, s[42:43]
	s_mov_b32 m0, s59
	ds_read_b128 v[216:219], v160 offset:33792
	global_load_lds_dwordx4 v142, s[42:43]
	ds_read_b128 v[220:223], v160 offset:34816
	ds_read_b128 v[224:227], v160 offset:35840
	ds_read_b128 v[228:231], v160 offset:36864
	ds_read_b128 v[232:235], v160 offset:37888
	ds_read_b128 v[236:239], v160 offset:38912
	ds_read_b128 v[240:243], v160 offset:39936
	s_waitcnt vmcnt(8)
	s_waitcnt lgkmcnt(8)
	s_barrier
	s_setprio 1
	s_waitcnt lgkmcnt(0)
	v_mfma_f32_16x16x32_bf16 v[128:131], v[164:167], v[212:215], v[128:131]
	v_mfma_f32_16x16x32_bf16 v[124:127], v[188:191], v[212:215], v[124:127]
	v_mfma_f32_16x16x32_bf16 v[112:115], v[164:167], v[220:223], v[112:115]
	v_mfma_f32_16x16x32_bf16 v[108:111], v[188:191], v[220:223], v[108:111]
	v_mfma_f32_16x16x32_bf16 v[96:99], v[164:167], v[228:231], v[96:99]
	v_mfma_f32_16x16x32_bf16 v[92:95], v[188:191], v[228:231], v[92:95]
	v_mfma_f32_16x16x32_bf16 v[80:83], v[164:167], v[236:239], v[80:83]
	v_mfma_f32_16x16x32_bf16 v[76:79], v[188:191], v[236:239], v[76:79]
	v_mfma_f32_16x16x32_bf16 v[128:131], v[168:171], v[216:219], v[128:131]
	v_mfma_f32_16x16x32_bf16 v[124:127], v[192:195], v[216:219], v[124:127]
	v_mfma_f32_16x16x32_bf16 v[112:115], v[168:171], v[224:227], v[112:115]
	v_mfma_f32_16x16x32_bf16 v[108:111], v[192:195], v[224:227], v[108:111]
	v_mfma_f32_16x16x32_bf16 v[96:99], v[168:171], v[232:235], v[96:99]
	v_mfma_f32_16x16x32_bf16 v[92:95], v[192:195], v[232:235], v[92:95]
	v_mfma_f32_16x16x32_bf16 v[80:83], v[168:171], v[240:243], v[80:83]
	v_mfma_f32_16x16x32_bf16 v[76:79], v[192:195], v[240:243], v[76:79]
	s_setprio 0
	s_setprio 1
	v_mfma_f32_16x16x32_bf16 v[120:123], v[196:199], v[212:215], v[120:123]
	v_mfma_f32_16x16x32_bf16 v[116:119], v[204:207], v[212:215], v[116:119]
	v_mfma_f32_16x16x32_bf16 v[104:107], v[196:199], v[220:223], v[104:107]
	v_mfma_f32_16x16x32_bf16 v[100:103], v[204:207], v[220:223], v[100:103]
	v_mfma_f32_16x16x32_bf16 v[88:91], v[196:199], v[228:231], v[88:91]
	v_mfma_f32_16x16x32_bf16 v[84:87], v[204:207], v[228:231], v[84:87]
	v_mfma_f32_16x16x32_bf16 v[72:75], v[196:199], v[236:239], v[72:75]
	v_mfma_f32_16x16x32_bf16 v[68:71], v[204:207], v[236:239], v[68:71]
	v_mfma_f32_16x16x32_bf16 v[120:123], v[200:203], v[216:219], v[120:123]
	v_mfma_f32_16x16x32_bf16 v[116:119], v[208:211], v[216:219], v[116:119]
	v_mfma_f32_16x16x32_bf16 v[104:107], v[200:203], v[224:227], v[104:107]
	v_mfma_f32_16x16x32_bf16 v[100:103], v[208:211], v[224:227], v[100:103]
	v_mfma_f32_16x16x32_bf16 v[88:91], v[200:203], v[232:235], v[88:91]
	v_mfma_f32_16x16x32_bf16 v[84:87], v[208:211], v[232:235], v[84:87]
	v_mfma_f32_16x16x32_bf16 v[72:75], v[200:203], v[240:243], v[72:75]
	v_mfma_f32_16x16x32_bf16 v[68:71], v[208:211], v[240:243], v[68:71]
	s_setprio 0
	s_barrier
	s_add_u32 s42, s48, 0x80
	s_addc_u32 s43, s49, 0
	s_add_i32 m0, s69, 0x18000
	s_add_u32 s46, s48, s53
	s_addc_u32 s47, s49, 0
	global_load_lds_dwordx4 v140, s[42:43]
	s_add_i32 m0, s69, 0x1a000
	ds_read_b128 v[212:215], v160 offset:49152
	global_load_lds_dwordx4 v144, s[42:43]
	s_add_i32 m0, s69, 0x1c000
	ds_read_b128 v[216:219], v160 offset:50176
	global_load_lds_dwordx4 v140, s[46:47]
	s_add_i32 m0, s69, 0x1e000
	ds_read_b128 v[220:223], v160 offset:51200
	global_load_lds_dwordx4 v144, s[46:47]
	ds_read_b128 v[224:227], v160 offset:52224
	ds_read_b128 v[228:231], v160 offset:53248
	ds_read_b128 v[232:235], v160 offset:54272
	ds_read_b128 v[236:239], v160 offset:55296
	ds_read_b128 v[240:243], v160 offset:56320
	s_waitcnt vmcnt(6)
	s_waitcnt lgkmcnt(0)
	s_barrier
	s_setprio 1
	s_waitcnt lgkmcnt(0)
	v_mfma_f32_16x16x32_bf16 v[64:67], v[164:167], v[212:215], v[64:67]
	v_mfma_f32_16x16x32_bf16 v[60:63], v[188:191], v[212:215], v[60:63]
	v_mfma_f32_16x16x32_bf16 v[48:51], v[164:167], v[220:223], v[48:51]
	v_mfma_f32_16x16x32_bf16 v[44:47], v[188:191], v[220:223], v[44:47]
	v_mfma_f32_16x16x32_bf16 v[32:35], v[164:167], v[228:231], v[32:35]
	v_mfma_f32_16x16x32_bf16 v[28:31], v[188:191], v[228:231], v[28:31]
	v_mfma_f32_16x16x32_bf16 v[16:19], v[164:167], v[236:239], v[16:19]
	v_mfma_f32_16x16x32_bf16 v[12:15], v[188:191], v[236:239], v[12:15]
	v_mfma_f32_16x16x32_bf16 v[64:67], v[168:171], v[216:219], v[64:67]
	v_mfma_f32_16x16x32_bf16 v[60:63], v[192:195], v[216:219], v[60:63]
	v_mfma_f32_16x16x32_bf16 v[48:51], v[168:171], v[224:227], v[48:51]
	v_mfma_f32_16x16x32_bf16 v[44:47], v[192:195], v[224:227], v[44:47]
	v_mfma_f32_16x16x32_bf16 v[32:35], v[168:171], v[232:235], v[32:35]
	v_mfma_f32_16x16x32_bf16 v[28:31], v[192:195], v[232:235], v[28:31]
	v_mfma_f32_16x16x32_bf16 v[16:19], v[168:171], v[240:243], v[16:19]
	v_mfma_f32_16x16x32_bf16 v[12:15], v[192:195], v[240:243], v[12:15]
	s_setprio 0
	s_setprio 1
	v_mfma_f32_16x16x32_bf16 v[56:59], v[196:199], v[212:215], v[56:59]
	v_mfma_f32_16x16x32_bf16 v[52:55], v[204:207], v[212:215], v[52:55]
	v_mfma_f32_16x16x32_bf16 v[40:43], v[196:199], v[220:223], v[40:43]
	v_mfma_f32_16x16x32_bf16 v[36:39], v[204:207], v[220:223], v[36:39]
	v_mfma_f32_16x16x32_bf16 v[24:27], v[196:199], v[228:231], v[24:27]
	v_mfma_f32_16x16x32_bf16 v[20:23], v[204:207], v[228:231], v[20:23]
	v_mfma_f32_16x16x32_bf16 v[8:11], v[196:199], v[236:239], v[8:11]
	v_mfma_f32_16x16x32_bf16 v[4:7], v[204:207], v[236:239], v[4:7]
	v_mfma_f32_16x16x32_bf16 v[56:59], v[200:203], v[216:219], v[56:59]
	v_mfma_f32_16x16x32_bf16 v[52:55], v[208:211], v[216:219], v[52:55]
	v_mfma_f32_16x16x32_bf16 v[40:43], v[200:203], v[224:227], v[40:43]
	v_mfma_f32_16x16x32_bf16 v[36:39], v[208:211], v[224:227], v[36:39]
	v_mfma_f32_16x16x32_bf16 v[24:27], v[200:203], v[232:235], v[24:27]
	v_mfma_f32_16x16x32_bf16 v[20:23], v[208:211], v[232:235], v[20:23]
	v_mfma_f32_16x16x32_bf16 v[8:11], v[200:203], v[240:243], v[8:11]
	v_mfma_f32_16x16x32_bf16 v[4:7], v[208:211], v[240:243], v[4:7]
	s_setprio 0
	s_barrier
	s_add_i32 s63, s63, 2
	s_add_u32 s28, s28, 0x100
	s_addc_u32 s29, s29, 0
	s_cmp_gt_u32 s63, s55
	s_mov_b64 s[42:43], s[44:45]

.Lg1_loop:
	s_add_u32 s44, s42, 0x100
	s_addc_u32 s45, s43, 0
	s_cmp_eq_u32 s63, s54
	s_cselect_b32 s50, s26, s44
	s_cselect_b32 s51, s5, s45
	s_cselect_b32 s48, s27, s28
	s_cselect_b32 s49, s23, s29
	s_add_u32 s46, s42, 0x80
	s_addc_u32 s47, s43, 0
	s_mov_b32 m0, s60
	s_add_u32 s42, s42, s53
	s_addc_u32 s43, s43, 0
	global_load_lds_dwordx4 v0, s[46:47]
	s_mov_b32 m0, s61
	ds_read_b128 v[164:167], v244
	global_load_lds_dwordx4 v142, s[46:47]
	ds_read_b128 v[168:171], v244 offset:1024
	ds_read_b128 v[188:191], v244 offset:2048
	ds_read_b128 v[192:195], v244 offset:3072
	ds_read_b128 v[196:199], v244 offset:16384
	ds_read_b128 v[200:203], v244 offset:17408
	ds_read_b128 v[204:207], v244 offset:18432
	ds_read_b128 v[208:211], v244 offset:19456
	s_add_i32 m0, s56, 0xc000
	ds_read_b128 v[212:215], v160
	global_load_lds_dwordx4 v0, s[42:43]
	s_add_i32 m0, s56, 0xe000
	ds_read_b128 v[216:219], v160 offset:1024
	global_load_lds_dwordx4 v142, s[42:43]
	ds_read_b128 v[220:223], v160 offset:2048
	ds_read_b128 v[224:227], v160 offset:3072
	ds_read_b128 v[228:231], v160 offset:4096
	ds_read_b128 v[232:235], v160 offset:5120
	ds_read_b128 v[236:239], v160 offset:6144
	ds_read_b128 v[240:243], v160 offset:7168
	s_waitcnt vmcnt(8)
	s_waitcnt lgkmcnt(8)
	s_barrier
	s_setprio 1
	s_waitcnt lgkmcnt(0)
	v_mfma_f32_16x16x32_bf16 v[128:131], v[164:167], v[212:215], v[128:131]
	v_mfma_f32_16x16x32_bf16 v[124:127], v[188:191], v[212:215], v[124:127]
	v_mfma_f32_16x16x32_bf16 v[112:115], v[164:167], v[220:223], v[112:115]
	v_mfma_f32_16x16x32_bf16 v[108:111], v[188:191], v[220:223], v[108:111]
	v_mfma_f32_16x16x32_bf16 v[96:99], v[164:167], v[228:231], v[96:99]
	v_mfma_f32_16x16x32_bf16 v[92:95], v[188:191], v[228:231], v[92:95]
	v_mfma_f32_16x16x32_bf16 v[80:83], v[164:167], v[236:239], v[80:83]
	v_mfma_f32_16x16x32_bf16 v[76:79], v[188:191], v[236:239], v[76:79]
	v_mfma_f32_16x16x32_bf16 v[128:131], v[168:171], v[216:219], v[128:131]
	v_mfma_f32_16x16x32_bf16 v[124:127], v[192:195], v[216:219], v[124:127]
	v_mfma_f32_16x16x32_bf16 v[112:115], v[168:171], v[224:227], v[112:115]
	v_mfma_f32_16x16x32_bf16 v[108:111], v[192:195], v[224:227], v[108:111]
	v_mfma_f32_16x16x32_bf16 v[96:99], v[168:171], v[232:235], v[96:99]
	v_mfma_f32_16x16x32_bf16 v[92:95], v[192:195], v[232:235], v[92:95]
	v_mfma_f32_16x16x32_bf16 v[80:83], v[168:171], v[240:243], v[80:83]
	v_mfma_f32_16x16x32_bf16 v[76:79], v[192:195], v[240:243], v[76:79]
	s_setprio 0
	s_setprio 1
	v_mfma_f32_16x16x32_bf16 v[120:123], v[196:199], v[212:215], v[120:123]
	v_mfma_f32_16x16x32_bf16 v[116:119], v[204:207], v[212:215], v[116:119]
	v_mfma_f32_16x16x32_bf16 v[104:107], v[196:199], v[220:223], v[104:107]
	v_mfma_f32_16x16x32_bf16 v[100:103], v[204:207], v[220:223], v[100:103]
	v_mfma_f32_16x16x32_bf16 v[88:91], v[196:199], v[228:231], v[88:91]
	v_mfma_f32_16x16x32_bf16 v[84:87], v[204:207], v[228:231], v[84:87]
	v_mfma_f32_16x16x32_bf16 v[72:75], v[196:199], v[236:239], v[72:75]
	v_mfma_f32_16x16x32_bf16 v[68:71], v[204:207], v[236:239], v[68:71]
	v_mfma_f32_16x16x32_bf16 v[120:123], v[200:203], v[216:219], v[120:123]
	v_mfma_f32_16x16x32_bf16 v[116:119], v[208:211], v[216:219], v[116:119]
	v_mfma_f32_16x16x32_bf16 v[104:107], v[200:203], v[224:227], v[104:107]
	v_mfma_f32_16x16x32_bf16 v[100:103], v[208:211], v[224:227], v[100:103]
	v_mfma_f32_16x16x32_bf16 v[88:91], v[200:203], v[232:235], v[88:91]
	v_mfma_f32_16x16x32_bf16 v[84:87], v[208:211], v[232:235], v[84:87]
	v_mfma_f32_16x16x32_bf16 v[72:75], v[200:203], v[240:243], v[72:75]
	v_mfma_f32_16x16x32_bf16 v[68:71], v[208:211], v[240:243], v[68:71]
	s_setprio 0
	s_barrier
	s_add_i32 m0, s69, 0x10000
	s_add_u32 s42, s48, s90
	s_addc_u32 s43, s49, 0
	global_load_lds_dwordx4 v140, s[48:49]
	s_add_i32 m0, s69, 0x12000
	ds_read_b128 v[212:215], v160 offset:16384
	global_load_lds_dwordx4 v144, s[48:49]
	s_add_i32 m0, s69, 0x14000
	ds_read_b128 v[216:219], v160 offset:17408
	global_load_lds_dwordx4 v140, s[42:43]
	s_add_i32 m0, s69, 0x16000
	ds_read_b128 v[220:223], v160 offset:18432
	global_load_lds_dwordx4 v144, s[42:43]
	ds_read_b128 v[224:227], v160 offset:19456
	ds_read_b128 v[228:231], v160 offset:20480
	ds_read_b128 v[232:235], v160 offset:21504
	ds_read_b128 v[236:239], v160 offset:22528
	ds_read_b128 v[240:243], v160 offset:23552
	s_waitcnt vmcnt(6)
	s_waitcnt lgkmcnt(0)
	s_barrier
	s_setprio 1
	s_waitcnt lgkmcnt(0)
	v_mfma_f32_16x16x32_bf16 v[64:67], v[164:167], v[212:215], v[64:67]
	v_mfma_f32_16x16x32_bf16 v[60:63], v[188:191], v[212:215], v[60:63]
	v_mfma_f32_16x16x32_bf16 v[48:51], v[164:167], v[220:223], v[48:51]
	v_mfma_f32_16x16x32_bf16 v[44:47], v[188:191], v[220:223], v[44:47]
	v_mfma_f32_16x16x32_bf16 v[32:35], v[164:167], v[228:231], v[32:35]
	v_mfma_f32_16x16x32_bf16 v[28:31], v[188:191], v[228:231], v[28:31]
	v_mfma_f32_16x16x32_bf16 v[16:19], v[164:167], v[236:239], v[16:19]
	v_mfma_f32_16x16x32_bf16 v[12:15], v[188:191], v[236:239], v[12:15]
	v_mfma_f32_16x16x32_bf16 v[64:67], v[168:171], v[216:219], v[64:67]
	v_mfma_f32_16x16x32_bf16 v[60:63], v[192:195], v[216:219], v[60:63]
	v_mfma_f32_16x16x32_bf16 v[48:51], v[168:171], v[224:227], v[48:51]
	v_mfma_f32_16x16x32_bf16 v[44:47], v[192:195], v[224:227], v[44:47]
	v_mfma_f32_16x16x32_bf16 v[32:35], v[168:171], v[232:235], v[32:35]
	v_mfma_f32_16x16x32_bf16 v[28:31], v[192:195], v[232:235], v[28:31]
	v_mfma_f32_16x16x32_bf16 v[16:19], v[168:171], v[240:243], v[16:19]
	v_mfma_f32_16x16x32_bf16 v[12:15], v[192:195], v[240:243], v[12:15]
	s_setprio 0
	s_setprio 1
	v_mfma_f32_16x16x32_bf16 v[56:59], v[196:199], v[212:215], v[56:59]
	v_mfma_f32_16x16x32_bf16 v[52:55], v[204:207], v[212:215], v[52:55]
	v_mfma_f32_16x16x32_bf16 v[40:43], v[196:199], v[220:223], v[40:43]
	v_mfma_f32_16x16x32_bf16 v[36:39], v[204:207], v[220:223], v[36:39]
	v_mfma_f32_16x16x32_bf16 v[24:27], v[196:199], v[228:231], v[24:27]
	v_mfma_f32_16x16x32_bf16 v[20:23], v[204:207], v[228:231], v[20:23]
	v_mfma_f32_16x16x32_bf16 v[8:11], v[196:199], v[236:239], v[8:11]
	v_mfma_f32_16x16x32_bf16 v[4:7], v[204:207], v[236:239], v[4:7]
	v_mfma_f32_16x16x32_bf16 v[56:59], v[200:203], v[216:219], v[56:59]
	v_mfma_f32_16x16x32_bf16 v[52:55], v[208:211], v[216:219], v[52:55]
	v_mfma_f32_16x16x32_bf16 v[40:43], v[200:203], v[224:227], v[40:43]
	v_mfma_f32_16x16x32_bf16 v[36:39], v[208:211], v[224:227], v[36:39]
	v_mfma_f32_16x16x32_bf16 v[24:27], v[200:203], v[232:235], v[24:27]
	v_mfma_f32_16x16x32_bf16 v[20:23], v[208:211], v[232:235], v[20:23]
	v_mfma_f32_16x16x32_bf16 v[8:11], v[200:203], v[240:243], v[8:11]
	v_mfma_f32_16x16x32_bf16 v[4:7], v[208:211], v[240:243], v[4:7]
	s_setprio 0
	s_barrier
	s_mov_b32 m0, s56
	s_add_u32 s42, s50, s90
	s_addc_u32 s43, s51, 0
	global_load_lds_dwordx4 v0, s[50:51]
	s_mov_b32 m0, s57
	ds_read_b128 v[164:167], v244 offset:32768
	global_load_lds_dwordx4 v142, s[50:51]
	ds_read_b128 v[168:171], v244 offset:33792
	ds_read_b128 v[188:191], v244 offset:34816
	ds_read_b128 v[192:195], v244 offset:35840
	ds_read_b128 v[196:199], v244 offset:49152
	ds_read_b128 v[200:203], v244 offset:50176
	ds_read_b128 v[204:207], v244 offset:51200
	ds_read_b128 v[208:211], v244 offset:52224
	s_mov_b32 m0, s58
	ds_read_b128 v[212:215], v160 offset:32768
	global_load_lds_dwordx4 v0, s[42:43]
	s_mov_b32 m0, s59
	ds_read_b128 v[216:219], v160 offset:33792
	global_load_lds_dwordx4 v142, s[42:43]
	ds_read_b128 v[220:223], v160 offset:34816
	ds_read_b128 v[224:227], v160 offset:35840
	ds_read_b128 v[228:231], v160 offset:36864
	ds_read_b128 v[232:235], v160 offset:37888
	ds_read_b128 v[236:239], v160 offset:38912
	ds_read_b128 v[240:243], v160 offset:39936
	s_waitcnt vmcnt(8)
	s_waitcnt lgkmcnt(8)
	s_barrier
	s_setprio 1
	s_waitcnt lgkmcnt(0)
	v_mfma_f32_16x16x32_bf16 v[128:131], v[164:167], v[212:215], v[128:131]
	v_mfma_f32_16x16x32_bf16 v[124:127], v[188:191], v[212:215], v[124:127]
	v_mfma_f32_16x16x32_bf16 v[112:115], v[164:167], v[220:223], v[112:115]
	v_mfma_f32_16x16x32_bf16 v[108:111], v[188:191], v[220:223], v[108:111]
	v_mfma_f32_16x16x32_bf16 v[96:99], v[164:167], v[228:231], v[96:99]
	v_mfma_f32_16x16x32_bf16 v[92:95], v[188:191], v[228:231], v[92:95]
	v_mfma_f32_16x16x32_bf16 v[80:83], v[164:167], v[236:239], v[80:83]
	v_mfma_f32_16x16x32_bf16 v[76:79], v[188:191], v[236:239], v[76:79]
	v_mfma_f32_16x16x32_bf16 v[128:131], v[168:171], v[216:219], v[128:131]
	v_mfma_f32_16x16x32_bf16 v[124:127], v[192:195], v[216:219], v[124:127]
	v_mfma_f32_16x16x32_bf16 v[112:115], v[168:171], v[224:227], v[112:115]
	v_mfma_f32_16x16x32_bf16 v[108:111], v[192:195], v[224:227], v[108:111]
	v_mfma_f32_16x16x32_bf16 v[96:99], v[168:171], v[232:235], v[96:99]
	v_mfma_f32_16x16x32_bf16 v[92:95], v[192:195], v[232:235], v[92:95]
	v_mfma_f32_16x16x32_bf16 v[80:83], v[168:171], v[240:243], v[80:83]
	v_mfma_f32_16x16x32_bf16 v[76:79], v[192:195], v[240:243], v[76:79]
	s_setprio 0
	s_setprio 1
	v_mfma_f32_16x16x32_bf16 v[120:123], v[196:199], v[212:215], v[120:123]
	v_mfma_f32_16x16x32_bf16 v[116:119], v[204:207], v[212:215], v[116:119]
	v_mfma_f32_16x16x32_bf16 v[104:107], v[196:199], v[220:223], v[104:107]
	v_mfma_f32_16x16x32_bf16 v[100:103], v[204:207], v[220:223], v[100:103]
	v_mfma_f32_16x16x32_bf16 v[88:91], v[196:199], v[228:231], v[88:91]
	v_mfma_f32_16x16x32_bf16 v[84:87], v[204:207], v[228:231], v[84:87]
	v_mfma_f32_16x16x32_bf16 v[72:75], v[196:199], v[236:239], v[72:75]
	v_mfma_f32_16x16x32_bf16 v[68:71], v[204:207], v[236:239], v[68:71]
	v_mfma_f32_16x16x32_bf16 v[120:123], v[200:203], v[216:219], v[120:123]
	v_mfma_f32_16x16x32_bf16 v[116:119], v[208:211], v[216:219], v[116:119]
	v_mfma_f32_16x16x32_bf16 v[104:107], v[200:203], v[224:227], v[104:107]
	v_mfma_f32_16x16x32_bf16 v[100:103], v[208:211], v[224:227], v[100:103]
	v_mfma_f32_16x16x32_bf16 v[88:91], v[200:203], v[232:235], v[88:91]
	v_mfma_f32_16x16x32_bf16 v[84:87], v[208:211], v[232:235], v[84:87]
	v_mfma_f32_16x16x32_bf16 v[72:75], v[200:203], v[240:243], v[72:75]
	v_mfma_f32_16x16x32_bf16 v[68:71], v[208:211], v[240:243], v[68:71]
	s_setprio 0
	s_barrier
	s_add_u32 s42, s48, 0x80
	s_addc_u32 s43, s49, 0
	s_add_i32 m0, s69, 0x18000
	s_add_u32 s46, s48, s53
	s_addc_u32 s47, s49, 0
	global_load_lds_dwordx4 v140, s[42:43]
	s_add_i32 m0, s69, 0x1a000
	ds_read_b128 v[212:215], v160 offset:49152
	global_load_lds_dwordx4 v144, s[42:43]
	s_add_i32 m0, s69, 0x1c000
	ds_read_b128 v[216:219], v160 offset:50176
	global_load_lds_dwordx4 v140, s[46:47]
	s_add_i32 m0, s69, 0x1e000
	ds_read_b128 v[220:223], v160 offset:51200
	global_load_lds_dwordx4 v144, s[46:47]
	ds_read_b128 v[224:227], v160 offset:52224
	ds_read_b128 v[228:231], v160 offset:53248
	ds_read_b128 v[232:235], v160 offset:54272
	ds_read_b128 v[236:239], v160 offset:55296
	ds_read_b128 v[240:243], v160 offset:56320
	s_waitcnt vmcnt(6)
	s_waitcnt lgkmcnt(0)
	s_barrier
	s_setprio 1
	s_waitcnt lgkmcnt(0)
	v_mfma_f32_16x16x32_bf16 v[64:67], v[164:167], v[212:215], v[64:67]
	v_mfma_f32_16x16x32_bf16 v[60:63], v[188:191], v[212:215], v[60:63]
	v_mfma_f32_16x16x32_bf16 v[48:51], v[164:167], v[220:223], v[48:51]
	v_mfma_f32_16x16x32_bf16 v[44:47], v[188:191], v[220:223], v[44:47]
	v_mfma_f32_16x16x32_bf16 v[32:35], v[164:167], v[228:231], v[32:35]
	v_mfma_f32_16x16x32_bf16 v[28:31], v[188:191], v[228:231], v[28:31]
	v_mfma_f32_16x16x32_bf16 v[16:19], v[164:167], v[236:239], v[16:19]
	v_mfma_f32_16x16x32_bf16 v[12:15], v[188:191], v[236:239], v[12:15]
	v_mfma_f32_16x16x32_bf16 v[64:67], v[168:171], v[216:219], v[64:67]
	v_mfma_f32_16x16x32_bf16 v[60:63], v[192:195], v[216:219], v[60:63]
	v_mfma_f32_16x16x32_bf16 v[48:51], v[168:171], v[224:227], v[48:51]
	v_mfma_f32_16x16x32_bf16 v[44:47], v[192:195], v[224:227], v[44:47]
	v_mfma_f32_16x16x32_bf16 v[32:35], v[168:171], v[232:235], v[32:35]
	v_mfma_f32_16x16x32_bf16 v[28:31], v[192:195], v[232:235], v[28:31]
	v_mfma_f32_16x16x32_bf16 v[16:19], v[168:171], v[240:243], v[16:19]
	v_mfma_f32_16x16x32_bf16 v[12:15], v[192:195], v[240:243], v[12:15]
	s_setprio 0
	s_setprio 1
	v_mfma_f32_16x16x32_bf16 v[56:59], v[196:199], v[212:215], v[56:59]
	v_mfma_f32_16x16x32_bf16 v[52:55], v[204:207], v[212:215], v[52:55]
	v_mfma_f32_16x16x32_bf16 v[40:43], v[196:199], v[220:223], v[40:43]
	v_mfma_f32_16x16x32_bf16 v[36:39], v[204:207], v[220:223], v[36:39]
	v_mfma_f32_16x16x32_bf16 v[24:27], v[196:199], v[228:231], v[24:27]
	v_mfma_f32_16x16x32_bf16 v[20:23], v[204:207], v[228:231], v[20:23]
	v_mfma_f32_16x16x32_bf16 v[8:11], v[196:199], v[236:239], v[8:11]
	v_mfma_f32_16x16x32_bf16 v[4:7], v[204:207], v[236:239], v[4:7]
	v_mfma_f32_16x16x32_bf16 v[56:59], v[200:203], v[216:219], v[56:59]
	v_mfma_f32_16x16x32_bf16 v[52:55], v[208:211], v[216:219], v[52:55]
	v_mfma_f32_16x16x32_bf16 v[40:43], v[200:203], v[224:227], v[40:43]
	v_mfma_f32_16x16x32_bf16 v[36:39], v[208:211], v[224:227], v[36:39]
	v_mfma_f32_16x16x32_bf16 v[24:27], v[200:203], v[232:235], v[24:27]
	v_mfma_f32_16x16x32_bf16 v[20:23], v[208:211], v[232:235], v[20:23]
	v_mfma_f32_16x16x32_bf16 v[8:11], v[200:203], v[240:243], v[8:11]
	v_mfma_f32_16x16x32_bf16 v[4:7], v[208:211], v[240:243], v[4:7]
	s_setprio 0
	s_barrier
	s_add_i32 s63, s63, 2
	s_add_u32 s28, s28, 0x100
	s_addc_u32 s29, s29, 0
	s_cmp_gt_u32 s63, s55
	s_mov_b64 s[42:43], s[44:45]
	s_cbranch_scc0 .Lg1_loop
	v_readlane_b32 s5, v250, 0
	v_readlane_b32 s23, v250, 1
	v_readlane_b32 s26, v250, 2
	v_readlane_b32 s27, v250, 3
	v_readlane_b32 s28, v250, 4
	v_readlane_b32 s29, v250, 5
	v_readlane_b32 s42, v250, 6
	v_readlane_b32 s43, v250, 7
	v_readlane_b32 s44, v250, 8
	v_readlane_b32 s45, v250, 9
	v_readlane_b32 s46, v250, 10
	v_readlane_b32 s47, v250, 11
	v_readlane_b32 s48, v250, 12
	v_readlane_b32 s49, v250, 13
	v_readlane_b32 s50, v250, 14
	v_readlane_b32 s51, v250, 15
	v_readlane_b32 s53, v250, 16
	v_readlane_b32 s54, v250, 17
	v_readlane_b32 s55, v250, 18
	v_readlane_b32 s56, v250, 19
	v_readlane_b32 s57, v250, 20
	v_readlane_b32 s58, v250, 21
	v_readlane_b32 s59, v250, 22
	v_readlane_b32 s60, v250, 23
	v_readlane_b32 s61, v250, 24
	v_readlane_b32 s63, v250, 25
	v_readlane_b32 s64, v250, 26
	v_readlane_b32 s65, v250, 27
	s_and_b64 vcc, exec, s[14:15]
	s_cbranch_vccz .LBB0_419
	s_barrier

.LBB0_499:
	v_add_u32_e32 v240, 0x10000, v3
	s_ashr_i32 s5, s4, 31
	s_lshl_b64 s[24:25], s[4:5], 19
	s_add_u32 s24, s52, s24
	s_addc_u32 s25, s53, s25
	s_and_b64 s[26:27], s[40:41], exec
	s_cselect_b32 s5, s25, s43
	s_cselect_b32 s26, s24, s42
	s_ashr_i32 s23, s22, 31
	s_lshl_b64 s[28:29], s[22:23], 19
	s_add_u32 s36, s54, s28
	s_addc_u32 s37, s55, s29
	s_and_b64 s[28:29], s[40:41], exec
	s_cselect_b32 s23, s37, s45
	s_cselect_b32 s27, s36, s44
	s_add_u32 s28, s44, 0x100
	v_mov_b32_e32 v4, 0
	s_addc_u32 s29, s45, 0
	s_mov_b32 s63, -2
	s_add_u32 s44, s42, 0x100
	s_addc_u32 s45, s43, 0
	s_cmp_eq_u32 s63, 12
	s_cselect_b32 s50, s26, s44
	s_cselect_b32 s51, s5, s45
	s_cselect_b32 s48, s27, s28
	s_cselect_b32 s49, s23, s29
	s_add_u32 s46, s42, 0x80
	s_addc_u32 s47, s43, 0
	s_mov_b32 m0, s60
	s_add_u32 s42, s42, 0x40080
	s_addc_u32 s43, s43, 0
	global_load_lds_dwordx4 v144, s[46:47]
	s_mov_b32 m0, s61
	ds_read_b128 v[146:149], v240
	global_load_lds_dwordx4 v140, s[46:47]
	ds_read_b128 v[150:153], v240 offset:1024
	ds_read_b128 v[154:157], v240 offset:2048
	ds_read_b128 v[158:161], v240 offset:3072
	ds_read_b128 v[162:165], v240 offset:16384
	ds_read_b128 v[166:169], v240 offset:17408
	ds_read_b128 v[170:173], v240 offset:18432
	ds_read_b128 v[186:189], v240 offset:19456
	s_add_i32 m0, s56, 0xc000
	ds_read_b128 v[190:193], v132
	global_load_lds_dwordx4 v144, s[42:43]
	s_add_i32 m0, s56, 0xe000
	ds_read_b128 v[194:197], v132 offset:1024
	global_load_lds_dwordx4 v140, s[42:43]
	ds_read_b128 v[198:201], v132 offset:2048
	ds_read_b128 v[202:205], v132 offset:3072
	ds_read_b128 v[206:209], v132 offset:4096
	ds_read_b128 v[210:213], v132 offset:5120
	ds_read_b128 v[214:217], v132 offset:6144
	ds_read_b128 v[218:221], v132 offset:7168
	s_waitcnt vmcnt(8)
	s_waitcnt lgkmcnt(8)
	s_barrier
	s_setprio 1
	s_waitcnt lgkmcnt(0)
	v_mfma_f32_16x16x32_bf16 v[128:131], v[146:149], v[190:193], 0
	v_mfma_f32_16x16x32_bf16 v[124:127], v[154:157], v[190:193], 0
	v_mfma_f32_16x16x32_bf16 v[112:115], v[146:149], v[198:201], 0
	v_mfma_f32_16x16x32_bf16 v[108:111], v[154:157], v[198:201], 0
	v_mfma_f32_16x16x32_bf16 v[96:99], v[146:149], v[206:209], 0
	v_mfma_f32_16x16x32_bf16 v[92:95], v[154:157], v[206:209], 0
	v_mfma_f32_16x16x32_bf16 v[80:83], v[146:149], v[214:217], 0
	v_mfma_f32_16x16x32_bf16 v[76:79], v[154:157], v[214:217], 0
	v_mfma_f32_16x16x32_bf16 v[128:131], v[150:153], v[194:197], v[128:131]
	v_mfma_f32_16x16x32_bf16 v[124:127], v[158:161], v[194:197], v[124:127]
	v_mfma_f32_16x16x32_bf16 v[112:115], v[150:153], v[202:205], v[112:115]
	v_mfma_f32_16x16x32_bf16 v[108:111], v[158:161], v[202:205], v[108:111]
	v_mfma_f32_16x16x32_bf16 v[96:99], v[150:153], v[210:213], v[96:99]
	v_mfma_f32_16x16x32_bf16 v[92:95], v[158:161], v[210:213], v[92:95]
	v_mfma_f32_16x16x32_bf16 v[80:83], v[150:153], v[218:221], v[80:83]
	v_mfma_f32_16x16x32_bf16 v[76:79], v[158:161], v[218:221], v[76:79]
	s_setprio 0
	s_setprio 1
	v_mfma_f32_16x16x32_bf16 v[120:123], v[162:165], v[190:193], 0
	v_mfma_f32_16x16x32_bf16 v[116:119], v[170:173], v[190:193], 0
	v_mfma_f32_16x16x32_bf16 v[104:107], v[162:165], v[198:201], 0
	v_mfma_f32_16x16x32_bf16 v[100:103], v[170:173], v[198:201], 0
	v_mfma_f32_16x16x32_bf16 v[88:91], v[162:165], v[206:209], 0
	v_mfma_f32_16x16x32_bf16 v[84:87], v[170:173], v[206:209], 0
	v_mfma_f32_16x16x32_bf16 v[72:75], v[162:165], v[214:217], 0
	v_mfma_f32_16x16x32_bf16 v[68:71], v[170:173], v[214:217], 0
	v_mfma_f32_16x16x32_bf16 v[120:123], v[166:169], v[194:197], v[120:123]
	v_mfma_f32_16x16x32_bf16 v[116:119], v[186:189], v[194:197], v[116:119]
	v_mfma_f32_16x16x32_bf16 v[104:107], v[166:169], v[202:205], v[104:107]
	v_mfma_f32_16x16x32_bf16 v[100:103], v[186:189], v[202:205], v[100:103]
	v_mfma_f32_16x16x32_bf16 v[88:91], v[166:169], v[210:213], v[88:91]
	v_mfma_f32_16x16x32_bf16 v[84:87], v[186:189], v[210:213], v[84:87]
	v_mfma_f32_16x16x32_bf16 v[72:75], v[166:169], v[218:221], v[72:75]
	v_mfma_f32_16x16x32_bf16 v[68:71], v[186:189], v[218:221], v[68:71]
	s_setprio 0
	s_barrier
	s_add_i32 m0, s69, 0x10000
	s_add_u32 s42, s48, 0x40000
	s_addc_u32 s43, s49, 0
	global_load_lds_dwordx4 v142, s[48:49]
	s_add_i32 m0, s69, 0x12000
	ds_read_b128 v[190:193], v132 offset:16384
	global_load_lds_dwordx4 v0, s[48:49]
	s_add_i32 m0, s69, 0x14000
	ds_read_b128 v[194:197], v132 offset:17408
	global_load_lds_dwordx4 v142, s[42:43]
	s_add_i32 m0, s69, 0x16000
	ds_read_b128 v[198:201], v132 offset:18432
	global_load_lds_dwordx4 v0, s[42:43]
	ds_read_b128 v[202:205], v132 offset:19456
	ds_read_b128 v[206:209], v132 offset:20480
	ds_read_b128 v[210:213], v132 offset:21504
	ds_read_b128 v[214:217], v132 offset:22528
	ds_read_b128 v[218:221], v132 offset:23552
	s_waitcnt vmcnt(6)
	s_waitcnt lgkmcnt(0)
	s_barrier
	s_setprio 1
	s_waitcnt lgkmcnt(0)
	v_mfma_f32_16x16x32_bf16 v[64:67], v[146:149], v[190:193], 0
	v_mfma_f32_16x16x32_bf16 v[60:63], v[154:157], v[190:193], 0
	v_mfma_f32_16x16x32_bf16 v[48:51], v[146:149], v[198:201], 0
	v_mfma_f32_16x16x32_bf16 v[44:47], v[154:157], v[198:201], 0
	v_mfma_f32_16x16x32_bf16 v[32:35], v[146:149], v[206:209], 0
	v_mfma_f32_16x16x32_bf16 v[28:31], v[154:157], v[206:209], 0
	v_mfma_f32_16x16x32_bf16 v[16:19], v[146:149], v[214:217], 0
	v_mfma_f32_16x16x32_bf16 v[12:15], v[154:157], v[214:217], 0
	v_mfma_f32_16x16x32_bf16 v[64:67], v[150:153], v[194:197], v[64:67]
	v_mfma_f32_16x16x32_bf16 v[60:63], v[158:161], v[194:197], v[60:63]
	v_mfma_f32_16x16x32_bf16 v[48:51], v[150:153], v[202:205], v[48:51]
	v_mfma_f32_16x16x32_bf16 v[44:47], v[158:161], v[202:205], v[44:47]
	v_mfma_f32_16x16x32_bf16 v[32:35], v[150:153], v[210:213], v[32:35]
	v_mfma_f32_16x16x32_bf16 v[28:31], v[158:161], v[210:213], v[28:31]
	v_mfma_f32_16x16x32_bf16 v[16:19], v[150:153], v[218:221], v[16:19]
	v_mfma_f32_16x16x32_bf16 v[12:15], v[158:161], v[218:221], v[12:15]
	s_setprio 0
	s_setprio 1
	v_mfma_f32_16x16x32_bf16 v[56:59], v[162:165], v[190:193], 0
	v_mfma_f32_16x16x32_bf16 v[52:55], v[170:173], v[190:193], 0
	v_mfma_f32_16x16x32_bf16 v[40:43], v[162:165], v[198:201], 0
	v_mfma_f32_16x16x32_bf16 v[36:39], v[170:173], v[198:201], 0
	v_mfma_f32_16x16x32_bf16 v[24:27], v[162:165], v[206:209], 0
	v_mfma_f32_16x16x32_bf16 v[20:23], v[170:173], v[206:209], 0
	v_mfma_f32_16x16x32_bf16 v[8:11], v[162:165], v[214:217], 0
	v_mfma_f32_16x16x32_bf16 v[4:7], v[170:173], v[214:217], 0
	v_mfma_f32_16x16x32_bf16 v[56:59], v[166:169], v[194:197], v[56:59]
	v_mfma_f32_16x16x32_bf16 v[52:55], v[186:189], v[194:197], v[52:55]
	v_mfma_f32_16x16x32_bf16 v[40:43], v[166:169], v[202:205], v[40:43]
	v_mfma_f32_16x16x32_bf16 v[36:39], v[186:189], v[202:205], v[36:39]
	v_mfma_f32_16x16x32_bf16 v[24:27], v[166:169], v[210:213], v[24:27]
	v_mfma_f32_16x16x32_bf16 v[20:23], v[186:189], v[210:213], v[20:23]
	v_mfma_f32_16x16x32_bf16 v[8:11], v[166:169], v[218:221], v[8:11]
	v_mfma_f32_16x16x32_bf16 v[4:7], v[186:189], v[218:221], v[4:7]
	s_setprio 0
	s_barrier
	s_mov_b32 m0, s56
	s_add_u32 s42, s50, 0x40000
	s_addc_u32 s43, s51, 0
	global_load_lds_dwordx4 v144, s[50:51]
	s_mov_b32 m0, s57
	ds_read_b128 v[146:149], v240 offset:32768
	global_load_lds_dwordx4 v140, s[50:51]
	ds_read_b128 v[150:153], v240 offset:33792
	ds_read_b128 v[154:157], v240 offset:34816
	ds_read_b128 v[158:161], v240 offset:35840
	ds_read_b128 v[162:165], v240 offset:49152
	ds_read_b128 v[166:169], v240 offset:50176
	ds_read_b128 v[170:173], v240 offset:51200
	ds_read_b128 v[186:189], v240 offset:52224
	s_mov_b32 m0, s58
	ds_read_b128 v[190:193], v132 offset:32768
	global_load_lds_dwordx4 v144, s[42:43]
	s_mov_b32 m0, s59
	ds_read_b128 v[194:197], v132 offset:33792
	global_load_lds_dwordx4 v140, s[42:43]
	ds_read_b128 v[198:201], v132 offset:34816
	ds_read_b128 v[202:205], v132 offset:35840
	ds_read_b128 v[206:209], v132 offset:36864
	ds_read_b128 v[210:213], v132 offset:37888
	ds_read_b128 v[214:217], v132 offset:38912
	ds_read_b128 v[218:221], v132 offset:39936
	s_waitcnt vmcnt(8)
	s_waitcnt lgkmcnt(8)
	s_barrier
	s_setprio 1
	s_waitcnt lgkmcnt(0)
	v_mfma_f32_16x16x32_bf16 v[128:131], v[146:149], v[190:193], v[128:131]
	v_mfma_f32_16x16x32_bf16 v[124:127], v[154:157], v[190:193], v[124:127]
	v_mfma_f32_16x16x32_bf16 v[112:115], v[146:149], v[198:201], v[112:115]
	v_mfma_f32_16x16x32_bf16 v[108:111], v[154:157], v[198:201], v[108:111]
	v_mfma_f32_16x16x32_bf16 v[96:99], v[146:149], v[206:209], v[96:99]
	v_mfma_f32_16x16x32_bf16 v[92:95], v[154:157], v[206:209], v[92:95]
	v_mfma_f32_16x16x32_bf16 v[80:83], v[146:149], v[214:217], v[80:83]
	v_mfma_f32_16x16x32_bf16 v[76:79], v[154:157], v[214:217], v[76:79]
	v_mfma_f32_16x16x32_bf16 v[128:131], v[150:153], v[194:197], v[128:131]
	v_mfma_f32_16x16x32_bf16 v[124:127], v[158:161], v[194:197], v[124:127]
	v_mfma_f32_16x16x32_bf16 v[112:115], v[150:153], v[202:205], v[112:115]
	v_mfma_f32_16x16x32_bf16 v[108:111], v[158:161], v[202:205], v[108:111]
	v_mfma_f32_16x16x32_bf16 v[96:99], v[150:153], v[210:213], v[96:99]
	v_mfma_f32_16x16x32_bf16 v[92:95], v[158:161], v[210:213], v[92:95]
	v_mfma_f32_16x16x32_bf16 v[80:83], v[150:153], v[218:221], v[80:83]
	v_mfma_f32_16x16x32_bf16 v[76:79], v[158:161], v[218:221], v[76:79]
	s_setprio 0
	s_setprio 1
	v_mfma_f32_16x16x32_bf16 v[120:123], v[162:165], v[190:193], v[120:123]
	v_mfma_f32_16x16x32_bf16 v[116:119], v[170:173], v[190:193], v[116:119]
	v_mfma_f32_16x16x32_bf16 v[104:107], v[162:165], v[198:201], v[104:107]
	v_mfma_f32_16x16x32_bf16 v[100:103], v[170:173], v[198:201], v[100:103]
	v_mfma_f32_16x16x32_bf16 v[88:91], v[162:165], v[206:209], v[88:91]
	v_mfma_f32_16x16x32_bf16 v[84:87], v[170:173], v[206:209], v[84:87]
	v_mfma_f32_16x16x32_bf16 v[72:75], v[162:165], v[214:217], v[72:75]
	v_mfma_f32_16x16x32_bf16 v[68:71], v[170:173], v[214:217], v[68:71]
	v_mfma_f32_16x16x32_bf16 v[120:123], v[166:169], v[194:197], v[120:123]
	v_mfma_f32_16x16x32_bf16 v[116:119], v[186:189], v[194:197], v[116:119]
	v_mfma_f32_16x16x32_bf16 v[104:107], v[166:169], v[202:205], v[104:107]
	v_mfma_f32_16x16x32_bf16 v[100:103], v[186:189], v[202:205], v[100:103]
	v_mfma_f32_16x16x32_bf16 v[88:91], v[166:169], v[210:213], v[88:91]
	v_mfma_f32_16x16x32_bf16 v[84:87], v[186:189], v[210:213], v[84:87]
	v_mfma_f32_16x16x32_bf16 v[72:75], v[166:169], v[218:221], v[72:75]
	v_mfma_f32_16x16x32_bf16 v[68:71], v[186:189], v[218:221], v[68:71]
	s_setprio 0
	s_barrier
	s_add_u32 s42, s48, 0x80
	s_addc_u32 s43, s49, 0
	s_add_i32 m0, s69, 0x18000
	s_add_u32 s46, s48, 0x40080
	s_addc_u32 s47, s49, 0
	global_load_lds_dwordx4 v142, s[42:43]
	s_add_i32 m0, s69, 0x1a000
	ds_read_b128 v[190:193], v132 offset:49152
	global_load_lds_dwordx4 v0, s[42:43]
	s_add_i32 m0, s69, 0x1c000
	ds_read_b128 v[194:197], v132 offset:50176
	global_load_lds_dwordx4 v142, s[46:47]
	s_add_i32 m0, s69, 0x1e000
	ds_read_b128 v[198:201], v132 offset:51200
	global_load_lds_dwordx4 v0, s[46:47]
	ds_read_b128 v[202:205], v132 offset:52224
	ds_read_b128 v[206:209], v132 offset:53248
	ds_read_b128 v[210:213], v132 offset:54272
	ds_read_b128 v[214:217], v132 offset:55296
	ds_read_b128 v[218:221], v132 offset:56320
	s_waitcnt vmcnt(6)
	s_waitcnt lgkmcnt(0)
	s_barrier
	s_setprio 1
	s_waitcnt lgkmcnt(0)
	v_mfma_f32_16x16x32_bf16 v[64:67], v[146:149], v[190:193], v[64:67]
	v_mfma_f32_16x16x32_bf16 v[60:63], v[154:157], v[190:193], v[60:63]
	v_mfma_f32_16x16x32_bf16 v[48:51], v[146:149], v[198:201], v[48:51]
	v_mfma_f32_16x16x32_bf16 v[44:47], v[154:157], v[198:201], v[44:47]
	v_mfma_f32_16x16x32_bf16 v[32:35], v[146:149], v[206:209], v[32:35]
	v_mfma_f32_16x16x32_bf16 v[28:31], v[154:157], v[206:209], v[28:31]
	v_mfma_f32_16x16x32_bf16 v[16:19], v[146:149], v[214:217], v[16:19]
	v_mfma_f32_16x16x32_bf16 v[12:15], v[154:157], v[214:217], v[12:15]
	v_mfma_f32_16x16x32_bf16 v[64:67], v[150:153], v[194:197], v[64:67]
	v_mfma_f32_16x16x32_bf16 v[60:63], v[158:161], v[194:197], v[60:63]
	v_mfma_f32_16x16x32_bf16 v[48:51], v[150:153], v[202:205], v[48:51]
	v_mfma_f32_16x16x32_bf16 v[44:47], v[158:161], v[202:205], v[44:47]
	v_mfma_f32_16x16x32_bf16 v[32:35], v[150:153], v[210:213], v[32:35]
	v_mfma_f32_16x16x32_bf16 v[28:31], v[158:161], v[210:213], v[28:31]
	v_mfma_f32_16x16x32_bf16 v[16:19], v[150:153], v[218:221], v[16:19]
	v_mfma_f32_16x16x32_bf16 v[12:15], v[158:161], v[218:221], v[12:15]
	s_setprio 0
	s_setprio 1
	v_mfma_f32_16x16x32_bf16 v[56:59], v[162:165], v[190:193], v[56:59]
	v_mfma_f32_16x16x32_bf16 v[52:55], v[170:173], v[190:193], v[52:55]
	v_mfma_f32_16x16x32_bf16 v[40:43], v[162:165], v[198:201], v[40:43]
	v_mfma_f32_16x16x32_bf16 v[36:39], v[170:173], v[198:201], v[36:39]
	v_mfma_f32_16x16x32_bf16 v[24:27], v[162:165], v[206:209], v[24:27]
	v_mfma_f32_16x16x32_bf16 v[20:23], v[170:173], v[206:209], v[20:23]
	v_mfma_f32_16x16x32_bf16 v[8:11], v[162:165], v[214:217], v[8:11]
	v_mfma_f32_16x16x32_bf16 v[4:7], v[170:173], v[214:217], v[4:7]
	v_mfma_f32_16x16x32_bf16 v[56:59], v[166:169], v[194:197], v[56:59]
	v_mfma_f32_16x16x32_bf16 v[52:55], v[186:189], v[194:197], v[52:55]
	v_mfma_f32_16x16x32_bf16 v[40:43], v[166:169], v[202:205], v[40:43]
	v_mfma_f32_16x16x32_bf16 v[36:39], v[186:189], v[202:205], v[36:39]
	v_mfma_f32_16x16x32_bf16 v[24:27], v[166:169], v[210:213], v[24:27]
	v_mfma_f32_16x16x32_bf16 v[20:23], v[186:189], v[210:213], v[20:23]
	v_mfma_f32_16x16x32_bf16 v[8:11], v[166:169], v[218:221], v[8:11]
	v_mfma_f32_16x16x32_bf16 v[4:7], v[186:189], v[218:221], v[4:7]
	s_setprio 0
	s_barrier
	s_add_i32 s63, s63, 2
	s_add_u32 s28, s28, 0x100
	s_addc_u32 s29, s29, 0
	s_cmp_gt_u32 s63, 13
	s_mov_b64 s[42:43], s[44:45]

.LBB0_500:
	s_add_u32 s44, s42, 0x100
	s_addc_u32 s45, s43, 0
	s_cmp_eq_u32 s63, 12
	s_cselect_b32 s50, s26, s44
	s_cselect_b32 s51, s5, s45
	s_cselect_b32 s48, s27, s28
	s_cselect_b32 s49, s23, s29
	s_add_u32 s46, s42, 0x80
	s_addc_u32 s47, s43, 0
	s_mov_b32 m0, s60
	s_add_u32 s42, s42, 0x40080
	s_addc_u32 s43, s43, 0
	global_load_lds_dwordx4 v144, s[46:47]
	s_mov_b32 m0, s61
	ds_read_b128 v[146:149], v240
	global_load_lds_dwordx4 v140, s[46:47]
	ds_read_b128 v[150:153], v240 offset:1024
	ds_read_b128 v[154:157], v240 offset:2048
	ds_read_b128 v[158:161], v240 offset:3072
	ds_read_b128 v[162:165], v240 offset:16384
	ds_read_b128 v[166:169], v240 offset:17408
	ds_read_b128 v[170:173], v240 offset:18432
	ds_read_b128 v[186:189], v240 offset:19456
	s_add_i32 m0, s56, 0xc000
	ds_read_b128 v[190:193], v132
	global_load_lds_dwordx4 v144, s[42:43]
	s_add_i32 m0, s56, 0xe000
	ds_read_b128 v[194:197], v132 offset:1024
	global_load_lds_dwordx4 v140, s[42:43]
	ds_read_b128 v[198:201], v132 offset:2048
	ds_read_b128 v[202:205], v132 offset:3072
	ds_read_b128 v[206:209], v132 offset:4096
	ds_read_b128 v[210:213], v132 offset:5120
	ds_read_b128 v[214:217], v132 offset:6144
	ds_read_b128 v[218:221], v132 offset:7168
	s_waitcnt vmcnt(8)
	s_waitcnt lgkmcnt(8)
	s_barrier
	s_setprio 1
	s_waitcnt lgkmcnt(0)
	v_mfma_f32_16x16x32_bf16 v[128:131], v[146:149], v[190:193], v[128:131]
	v_mfma_f32_16x16x32_bf16 v[124:127], v[154:157], v[190:193], v[124:127]
	v_mfma_f32_16x16x32_bf16 v[112:115], v[146:149], v[198:201], v[112:115]
	v_mfma_f32_16x16x32_bf16 v[108:111], v[154:157], v[198:201], v[108:111]
	v_mfma_f32_16x16x32_bf16 v[96:99], v[146:149], v[206:209], v[96:99]
	v_mfma_f32_16x16x32_bf16 v[92:95], v[154:157], v[206:209], v[92:95]
	v_mfma_f32_16x16x32_bf16 v[80:83], v[146:149], v[214:217], v[80:83]
	v_mfma_f32_16x16x32_bf16 v[76:79], v[154:157], v[214:217], v[76:79]
	v_mfma_f32_16x16x32_bf16 v[128:131], v[150:153], v[194:197], v[128:131]
	v_mfma_f32_16x16x32_bf16 v[124:127], v[158:161], v[194:197], v[124:127]
	v_mfma_f32_16x16x32_bf16 v[112:115], v[150:153], v[202:205], v[112:115]
	v_mfma_f32_16x16x32_bf16 v[108:111], v[158:161], v[202:205], v[108:111]
	v_mfma_f32_16x16x32_bf16 v[96:99], v[150:153], v[210:213], v[96:99]
	v_mfma_f32_16x16x32_bf16 v[92:95], v[158:161], v[210:213], v[92:95]
	v_mfma_f32_16x16x32_bf16 v[80:83], v[150:153], v[218:221], v[80:83]
	v_mfma_f32_16x16x32_bf16 v[76:79], v[158:161], v[218:221], v[76:79]
	s_setprio 0
	s_setprio 1
	v_mfma_f32_16x16x32_bf16 v[120:123], v[162:165], v[190:193], v[120:123]
	v_mfma_f32_16x16x32_bf16 v[116:119], v[170:173], v[190:193], v[116:119]
	v_mfma_f32_16x16x32_bf16 v[104:107], v[162:165], v[198:201], v[104:107]
	v_mfma_f32_16x16x32_bf16 v[100:103], v[170:173], v[198:201], v[100:103]
	v_mfma_f32_16x16x32_bf16 v[88:91], v[162:165], v[206:209], v[88:91]
	v_mfma_f32_16x16x32_bf16 v[84:87], v[170:173], v[206:209], v[84:87]
	v_mfma_f32_16x16x32_bf16 v[72:75], v[162:165], v[214:217], v[72:75]
	v_mfma_f32_16x16x32_bf16 v[68:71], v[170:173], v[214:217], v[68:71]
	v_mfma_f32_16x16x32_bf16 v[120:123], v[166:169], v[194:197], v[120:123]
	v_mfma_f32_16x16x32_bf16 v[116:119], v[186:189], v[194:197], v[116:119]
	v_mfma_f32_16x16x32_bf16 v[104:107], v[166:169], v[202:205], v[104:107]
	v_mfma_f32_16x16x32_bf16 v[100:103], v[186:189], v[202:205], v[100:103]
	v_mfma_f32_16x16x32_bf16 v[88:91], v[166:169], v[210:213], v[88:91]
	v_mfma_f32_16x16x32_bf16 v[84:87], v[186:189], v[210:213], v[84:87]
	v_mfma_f32_16x16x32_bf16 v[72:75], v[166:169], v[218:221], v[72:75]
	v_mfma_f32_16x16x32_bf16 v[68:71], v[186:189], v[218:221], v[68:71]
	s_setprio 0
	s_barrier
	s_add_i32 m0, s69, 0x10000
	s_add_u32 s42, s48, 0x40000
	s_addc_u32 s43, s49, 0
	global_load_lds_dwordx4 v142, s[48:49]
	s_add_i32 m0, s69, 0x12000
	ds_read_b128 v[190:193], v132 offset:16384
	global_load_lds_dwordx4 v0, s[48:49]
	s_add_i32 m0, s69, 0x14000
	ds_read_b128 v[194:197], v132 offset:17408
	global_load_lds_dwordx4 v142, s[42:43]
	s_add_i32 m0, s69, 0x16000
	ds_read_b128 v[198:201], v132 offset:18432
	global_load_lds_dwordx4 v0, s[42:43]
	ds_read_b128 v[202:205], v132 offset:19456
	ds_read_b128 v[206:209], v132 offset:20480
	ds_read_b128 v[210:213], v132 offset:21504
	ds_read_b128 v[214:217], v132 offset:22528
	ds_read_b128 v[218:221], v132 offset:23552
	s_waitcnt vmcnt(6)
	s_waitcnt lgkmcnt(0)
	s_barrier
	s_setprio 1
	s_waitcnt lgkmcnt(0)
	v_mfma_f32_16x16x32_bf16 v[64:67], v[146:149], v[190:193], v[64:67]
	v_mfma_f32_16x16x32_bf16 v[60:63], v[154:157], v[190:193], v[60:63]
	v_mfma_f32_16x16x32_bf16 v[48:51], v[146:149], v[198:201], v[48:51]
	v_mfma_f32_16x16x32_bf16 v[44:47], v[154:157], v[198:201], v[44:47]
	v_mfma_f32_16x16x32_bf16 v[32:35], v[146:149], v[206:209], v[32:35]
	v_mfma_f32_16x16x32_bf16 v[28:31], v[154:157], v[206:209], v[28:31]
	v_mfma_f32_16x16x32_bf16 v[16:19], v[146:149], v[214:217], v[16:19]
	v_mfma_f32_16x16x32_bf16 v[12:15], v[154:157], v[214:217], v[12:15]
	v_mfma_f32_16x16x32_bf16 v[64:67], v[150:153], v[194:197], v[64:67]
	v_mfma_f32_16x16x32_bf16 v[60:63], v[158:161], v[194:197], v[60:63]
	v_mfma_f32_16x16x32_bf16 v[48:51], v[150:153], v[202:205], v[48:51]
	v_mfma_f32_16x16x32_bf16 v[44:47], v[158:161], v[202:205], v[44:47]
	v_mfma_f32_16x16x32_bf16 v[32:35], v[150:153], v[210:213], v[32:35]
	v_mfma_f32_16x16x32_bf16 v[28:31], v[158:161], v[210:213], v[28:31]
	v_mfma_f32_16x16x32_bf16 v[16:19], v[150:153], v[218:221], v[16:19]
	v_mfma_f32_16x16x32_bf16 v[12:15], v[158:161], v[218:221], v[12:15]
	s_setprio 0
	s_setprio 1
	v_mfma_f32_16x16x32_bf16 v[56:59], v[162:165], v[190:193], v[56:59]
	v_mfma_f32_16x16x32_bf16 v[52:55], v[170:173], v[190:193], v[52:55]
	v_mfma_f32_16x16x32_bf16 v[40:43], v[162:165], v[198:201], v[40:43]
	v_mfma_f32_16x16x32_bf16 v[36:39], v[170:173], v[198:201], v[36:39]
	v_mfma_f32_16x16x32_bf16 v[24:27], v[162:165], v[206:209], v[24:27]
	v_mfma_f32_16x16x32_bf16 v[20:23], v[170:173], v[206:209], v[20:23]
	v_mfma_f32_16x16x32_bf16 v[8:11], v[162:165], v[214:217], v[8:11]
	v_mfma_f32_16x16x32_bf16 v[4:7], v[170:173], v[214:217], v[4:7]
	v_mfma_f32_16x16x32_bf16 v[56:59], v[166:169], v[194:197], v[56:59]
	v_mfma_f32_16x16x32_bf16 v[52:55], v[186:189], v[194:197], v[52:55]
	v_mfma_f32_16x16x32_bf16 v[40:43], v[166:169], v[202:205], v[40:43]
	v_mfma_f32_16x16x32_bf16 v[36:39], v[186:189], v[202:205], v[36:39]
	v_mfma_f32_16x16x32_bf16 v[24:27], v[166:169], v[210:213], v[24:27]
	v_mfma_f32_16x16x32_bf16 v[20:23], v[186:189], v[210:213], v[20:23]
	v_mfma_f32_16x16x32_bf16 v[8:11], v[166:169], v[218:221], v[8:11]
	v_mfma_f32_16x16x32_bf16 v[4:7], v[186:189], v[218:221], v[4:7]
	s_setprio 0
	s_barrier
	s_mov_b32 m0, s56
	s_add_u32 s42, s50, 0x40000
	s_addc_u32 s43, s51, 0
	global_load_lds_dwordx4 v144, s[50:51]
	s_mov_b32 m0, s57
	ds_read_b128 v[146:149], v240 offset:32768
	global_load_lds_dwordx4 v140, s[50:51]
	ds_read_b128 v[150:153], v240 offset:33792
	ds_read_b128 v[154:157], v240 offset:34816
	ds_read_b128 v[158:161], v240 offset:35840
	ds_read_b128 v[162:165], v240 offset:49152
	ds_read_b128 v[166:169], v240 offset:50176
	ds_read_b128 v[170:173], v240 offset:51200
	ds_read_b128 v[186:189], v240 offset:52224
	s_mov_b32 m0, s58
	ds_read_b128 v[190:193], v132 offset:32768
	global_load_lds_dwordx4 v144, s[42:43]
	s_mov_b32 m0, s59
	ds_read_b128 v[194:197], v132 offset:33792
	global_load_lds_dwordx4 v140, s[42:43]
	ds_read_b128 v[198:201], v132 offset:34816
	ds_read_b128 v[202:205], v132 offset:35840
	ds_read_b128 v[206:209], v132 offset:36864
	ds_read_b128 v[210:213], v132 offset:37888
	ds_read_b128 v[214:217], v132 offset:38912
	ds_read_b128 v[218:221], v132 offset:39936
	s_waitcnt vmcnt(8)
	s_waitcnt lgkmcnt(8)
	s_barrier
	s_setprio 1
	s_waitcnt lgkmcnt(0)
	v_mfma_f32_16x16x32_bf16 v[128:131], v[146:149], v[190:193], v[128:131]
	v_mfma_f32_16x16x32_bf16 v[124:127], v[154:157], v[190:193], v[124:127]
	v_mfma_f32_16x16x32_bf16 v[112:115], v[146:149], v[198:201], v[112:115]
	v_mfma_f32_16x16x32_bf16 v[108:111], v[154:157], v[198:201], v[108:111]
	v_mfma_f32_16x16x32_bf16 v[96:99], v[146:149], v[206:209], v[96:99]
	v_mfma_f32_16x16x32_bf16 v[92:95], v[154:157], v[206:209], v[92:95]
	v_mfma_f32_16x16x32_bf16 v[80:83], v[146:149], v[214:217], v[80:83]
	v_mfma_f32_16x16x32_bf16 v[76:79], v[154:157], v[214:217], v[76:79]
	v_mfma_f32_16x16x32_bf16 v[128:131], v[150:153], v[194:197], v[128:131]
	v_mfma_f32_16x16x32_bf16 v[124:127], v[158:161], v[194:197], v[124:127]
	v_mfma_f32_16x16x32_bf16 v[112:115], v[150:153], v[202:205], v[112:115]
	v_mfma_f32_16x16x32_bf16 v[108:111], v[158:161], v[202:205], v[108:111]
	v_mfma_f32_16x16x32_bf16 v[96:99], v[150:153], v[210:213], v[96:99]
	v_mfma_f32_16x16x32_bf16 v[92:95], v[158:161], v[210:213], v[92:95]
	v_mfma_f32_16x16x32_bf16 v[80:83], v[150:153], v[218:221], v[80:83]
	v_mfma_f32_16x16x32_bf16 v[76:79], v[158:161], v[218:221], v[76:79]
	s_setprio 0
	s_setprio 1
	v_mfma_f32_16x16x32_bf16 v[120:123], v[162:165], v[190:193], v[120:123]
	v_mfma_f32_16x16x32_bf16 v[116:119], v[170:173], v[190:193], v[116:119]
	v_mfma_f32_16x16x32_bf16 v[104:107], v[162:165], v[198:201], v[104:107]
	v_mfma_f32_16x16x32_bf16 v[100:103], v[170:173], v[198:201], v[100:103]
	v_mfma_f32_16x16x32_bf16 v[88:91], v[162:165], v[206:209], v[88:91]
	v_mfma_f32_16x16x32_bf16 v[84:87], v[170:173], v[206:209], v[84:87]
	v_mfma_f32_16x16x32_bf16 v[72:75], v[162:165], v[214:217], v[72:75]
	v_mfma_f32_16x16x32_bf16 v[68:71], v[170:173], v[214:217], v[68:71]
	v_mfma_f32_16x16x32_bf16 v[120:123], v[166:169], v[194:197], v[120:123]
	v_mfma_f32_16x16x32_bf16 v[116:119], v[186:189], v[194:197], v[116:119]
	v_mfma_f32_16x16x32_bf16 v[104:107], v[166:169], v[202:205], v[104:107]
	v_mfma_f32_16x16x32_bf16 v[100:103], v[186:189], v[202:205], v[100:103]
	v_mfma_f32_16x16x32_bf16 v[88:91], v[166:169], v[210:213], v[88:91]
	v_mfma_f32_16x16x32_bf16 v[84:87], v[186:189], v[210:213], v[84:87]
	v_mfma_f32_16x16x32_bf16 v[72:75], v[166:169], v[218:221], v[72:75]
	v_mfma_f32_16x16x32_bf16 v[68:71], v[186:189], v[218:221], v[68:71]
	s_setprio 0
	s_barrier
	s_add_u32 s42, s48, 0x80
	s_addc_u32 s43, s49, 0
	s_add_i32 m0, s69, 0x18000
	s_add_u32 s46, s48, 0x40080
	s_addc_u32 s47, s49, 0
	global_load_lds_dwordx4 v142, s[42:43]
	s_add_i32 m0, s69, 0x1a000
	ds_read_b128 v[190:193], v132 offset:49152
	global_load_lds_dwordx4 v0, s[42:43]
	s_add_i32 m0, s69, 0x1c000
	ds_read_b128 v[194:197], v132 offset:50176
	global_load_lds_dwordx4 v142, s[46:47]
	s_add_i32 m0, s69, 0x1e000
	ds_read_b128 v[198:201], v132 offset:51200
	global_load_lds_dwordx4 v0, s[46:47]
	ds_read_b128 v[202:205], v132 offset:52224
	ds_read_b128 v[206:209], v132 offset:53248
	ds_read_b128 v[210:213], v132 offset:54272
	ds_read_b128 v[214:217], v132 offset:55296
	ds_read_b128 v[218:221], v132 offset:56320
	s_waitcnt vmcnt(6)
	s_waitcnt lgkmcnt(0)
	s_barrier
	s_setprio 1
	s_waitcnt lgkmcnt(0)
	v_mfma_f32_16x16x32_bf16 v[64:67], v[146:149], v[190:193], v[64:67]
	v_mfma_f32_16x16x32_bf16 v[60:63], v[154:157], v[190:193], v[60:63]
	v_mfma_f32_16x16x32_bf16 v[48:51], v[146:149], v[198:201], v[48:51]
	v_mfma_f32_16x16x32_bf16 v[44:47], v[154:157], v[198:201], v[44:47]
	v_mfma_f32_16x16x32_bf16 v[32:35], v[146:149], v[206:209], v[32:35]
	v_mfma_f32_16x16x32_bf16 v[28:31], v[154:157], v[206:209], v[28:31]
	v_mfma_f32_16x16x32_bf16 v[16:19], v[146:149], v[214:217], v[16:19]
	v_mfma_f32_16x16x32_bf16 v[12:15], v[154:157], v[214:217], v[12:15]
	v_mfma_f32_16x16x32_bf16 v[64:67], v[150:153], v[194:197], v[64:67]
	v_mfma_f32_16x16x32_bf16 v[60:63], v[158:161], v[194:197], v[60:63]
	v_mfma_f32_16x16x32_bf16 v[48:51], v[150:153], v[202:205], v[48:51]
	v_mfma_f32_16x16x32_bf16 v[44:47], v[158:161], v[202:205], v[44:47]
	v_mfma_f32_16x16x32_bf16 v[32:35], v[150:153], v[210:213], v[32:35]
	v_mfma_f32_16x16x32_bf16 v[28:31], v[158:161], v[210:213], v[28:31]
	v_mfma_f32_16x16x32_bf16 v[16:19], v[150:153], v[218:221], v[16:19]
	v_mfma_f32_16x16x32_bf16 v[12:15], v[158:161], v[218:221], v[12:15]
	s_setprio 0
	s_setprio 1
	v_mfma_f32_16x16x32_bf16 v[56:59], v[162:165], v[190:193], v[56:59]
	v_mfma_f32_16x16x32_bf16 v[52:55], v[170:173], v[190:193], v[52:55]
	v_mfma_f32_16x16x32_bf16 v[40:43], v[162:165], v[198:201], v[40:43]
	v_mfma_f32_16x16x32_bf16 v[36:39], v[170:173], v[198:201], v[36:39]
	v_mfma_f32_16x16x32_bf16 v[24:27], v[162:165], v[206:209], v[24:27]
	v_mfma_f32_16x16x32_bf16 v[20:23], v[170:173], v[206:209], v[20:23]
	v_mfma_f32_16x16x32_bf16 v[8:11], v[162:165], v[214:217], v[8:11]
	v_mfma_f32_16x16x32_bf16 v[4:7], v[170:173], v[214:217], v[4:7]
	v_mfma_f32_16x16x32_bf16 v[56:59], v[166:169], v[194:197], v[56:59]
	v_mfma_f32_16x16x32_bf16 v[52:55], v[186:189], v[194:197], v[52:55]
	v_mfma_f32_16x16x32_bf16 v[40:43], v[166:169], v[202:205], v[40:43]
	v_mfma_f32_16x16x32_bf16 v[36:39], v[186:189], v[202:205], v[36:39]
	v_mfma_f32_16x16x32_bf16 v[24:27], v[166:169], v[210:213], v[24:27]
	v_mfma_f32_16x16x32_bf16 v[20:23], v[186:189], v[210:213], v[20:23]
	v_mfma_f32_16x16x32_bf16 v[8:11], v[166:169], v[218:221], v[8:11]
	v_mfma_f32_16x16x32_bf16 v[4:7], v[186:189], v[218:221], v[4:7]
	s_setprio 0
	s_barrier
	s_add_i32 s63, s63, 2
	s_add_u32 s28, s28, 0x100
	s_addc_u32 s29, s29, 0
	s_cmp_gt_u32 s63, 13
	s_mov_b64 s[42:43], s[44:45]
	s_cbranch_scc0 .LBB0_500
	s_and_b64 vcc, exec, s[14:15]
	s_cbranch_vccz .LBB0_503
	s_barrier
